# layer-0 memory-attention copy: Q loads issued before staging, prefetch no longer forced complete by the Q waits (counted vmcnt)
# speedup vs baseline: 1.0149x; 1.0057x over previous
.LBB0_613:
	ds_read_b128 v[44:47], v128
	ds_read_b128 v[48:51], v128 offset:64
	s_mov_b32 s9, 0xff61b1e6
	s_waitcnt vmcnt(11) lgkmcnt(1)
	v_mfma_f32_16x16x32_bf16 v[44:47], v[44:47], v[108:111], 0
	ds_read_b128 v[52:55], v128 offset:27712
	ds_read_b128 v[56:59], v128 offset:30016
	ds_read_b128 v[130:133], v128 offset:32320
	s_waitcnt vmcnt(10) lgkmcnt(3)
	v_mfma_f32_16x16x32_bf16 v[104:107], v[48:51], v[60:63], v[44:47]
	ds_read_b128 v[48:51], v128 offset:2368
	s_nop 1
	ds_read_b128 v[44:47], v128 offset:2304
	s_waitcnt lgkmcnt(0)
	v_mfma_f32_16x16x32_bf16 v[44:47], v[44:47], v[108:111], 0
	v_mfma_f32_16x16x32_bf16 v[100:103], v[48:51], v[60:63], v[44:47]
	ds_read_b128 v[48:51], v128 offset:4672
	s_nop 5
	ds_read_b128 v[44:47], v128 offset:4608
	s_waitcnt lgkmcnt(0)
	v_mfma_f32_16x16x32_bf16 v[44:47], v[44:47], v[108:111], 0
	v_mfma_f32_16x16x32_bf16 v[96:99], v[48:51], v[60:63], v[44:47]
	ds_read_b128 v[48:51], v128 offset:6976
	s_nop 5
	ds_read_b128 v[44:47], v128 offset:6912
	s_waitcnt lgkmcnt(0)
	v_mfma_f32_16x16x32_bf16 v[44:47], v[44:47], v[108:111], 0
	v_mfma_f32_16x16x32_bf16 v[92:95], v[48:51], v[60:63], v[44:47]
	ds_read_b128 v[48:51], v128 offset:9280
	s_nop 5
	ds_read_b128 v[44:47], v128 offset:9216
	s_waitcnt lgkmcnt(0)
	v_mfma_f32_16x16x32_bf16 v[44:47], v[44:47], v[108:111], 0
	v_mfma_f32_16x16x32_bf16 v[88:91], v[48:51], v[60:63], v[44:47]
	ds_read_b128 v[48:51], v128 offset:11584
	s_nop 5
	ds_read_b128 v[44:47], v128 offset:11520
	s_waitcnt lgkmcnt(0)
	v_mfma_f32_16x16x32_bf16 v[44:47], v[44:47], v[108:111], 0
	v_mfma_f32_16x16x32_bf16 v[84:87], v[48:51], v[60:63], v[44:47]
	ds_read_b128 v[48:51], v128 offset:13888
	s_nop 5
	ds_read_b128 v[44:47], v128 offset:13824
	s_waitcnt lgkmcnt(0)
	v_mfma_f32_16x16x32_bf16 v[44:47], v[44:47], v[108:111], 0
	v_mfma_f32_16x16x32_bf16 v[80:83], v[48:51], v[60:63], v[44:47]
	ds_read_b128 v[48:51], v128 offset:16192
	s_nop 5
	ds_read_b128 v[44:47], v128 offset:16128
	s_waitcnt lgkmcnt(0)
	v_mfma_f32_16x16x32_bf16 v[44:47], v[44:47], v[108:111], 0
	v_mfma_f32_16x16x32_bf16 v[76:79], v[48:51], v[60:63], v[44:47]
	ds_read_b128 v[48:51], v128 offset:18496
	s_nop 5
	ds_read_b128 v[44:47], v128 offset:18432
	s_waitcnt lgkmcnt(0)
	v_mfma_f32_16x16x32_bf16 v[44:47], v[44:47], v[108:111], 0
	v_mfma_f32_16x16x32_bf16 v[72:75], v[48:51], v[60:63], v[44:47]
	ds_read_b128 v[48:51], v128 offset:20800
	s_nop 5
	ds_read_b128 v[44:47], v128 offset:20736
	s_waitcnt lgkmcnt(0)
	v_mfma_f32_16x16x32_bf16 v[44:47], v[44:47], v[108:111], 0
	v_mfma_f32_16x16x32_bf16 v[68:71], v[48:51], v[60:63], v[44:47]
	ds_read_b128 v[48:51], v128 offset:23104
	s_nop 5
	ds_read_b128 v[44:47], v128 offset:23040
	s_waitcnt lgkmcnt(0)
	v_mfma_f32_16x16x32_bf16 v[44:47], v[44:47], v[108:111], 0
	v_mfma_f32_16x16x32_bf16 v[64:67], v[48:51], v[60:63], v[44:47]
	ds_read_b128 v[48:51], v128 offset:25408
	s_nop 5
	ds_read_b128 v[44:47], v128 offset:25344
	s_waitcnt lgkmcnt(0)
	v_mfma_f32_16x16x32_bf16 v[44:47], v[44:47], v[108:111], 0
	v_mfma_f32_16x16x32_bf16 v[44:47], v[48:51], v[60:63], v[44:47]
	ds_read_b128 v[48:51], v128 offset:27648
	s_waitcnt lgkmcnt(0)
	v_mfma_f32_16x16x32_bf16 v[48:51], v[48:51], v[108:111], 0
	v_mfma_f32_16x16x32_bf16 v[48:51], v[52:55], v[60:63], v[48:51]
	ds_read_b128 v[52:55], v128 offset:29952
	s_waitcnt lgkmcnt(0)
	v_mfma_f32_16x16x32_bf16 v[52:55], v[52:55], v[108:111], 0
	v_mfma_f32_16x16x32_bf16 v[52:55], v[56:59], v[60:63], v[52:55]
	ds_read_b128 v[56:59], v128 offset:32256
	s_waitcnt lgkmcnt(0)
	v_mfma_f32_16x16x32_bf16 v[56:59], v[56:59], v[108:111], 0
	v_mfma_f32_16x16x32_bf16 v[56:59], v[130:133], v[60:63], v[56:59]
	ds_read_b128 v[130:133], v128 offset:34560
	s_waitcnt lgkmcnt(0)
	v_mfma_f32_16x16x32_bf16 v[108:111], v[130:133], v[108:111], 0
	ds_read_b128 v[130:133], v128 offset:34624
	s_waitcnt lgkmcnt(0)
	v_mfma_f32_16x16x32_bf16 v[60:63], v[130:133], v[60:63], v[108:111]
	s_nop 4
	v_max_f32_e32 v108, v105, v105
	v_max_f32_e32 v109, v104, v104
	v_max_f32_e32 v108, v109, v108
	v_max_f32_e32 v109, v107, v107
	v_max_f32_e32 v110, v106, v106
	v_max_f32_e32 v109, v110, v109
	v_max3_f32 v108, v108, v109, s9
	v_max_f32_e32 v109, v101, v101
	v_max_f32_e32 v110, v100, v100
	v_max_f32_e32 v109, v110, v109
	v_max_f32_e32 v110, v103, v103
	v_max_f32_e32 v111, v102, v102
	v_max_f32_e32 v110, v111, v110
	v_max3_f32 v108, v109, v110, v108
	v_max_f32_e32 v109, v97, v97
	v_max_f32_e32 v110, v96, v96
	v_max_f32_e32 v109, v110, v109
	v_max_f32_e32 v110, v99, v99
	v_max_f32_e32 v111, v98, v98
	v_max_f32_e32 v110, v111, v110
	v_max3_f32 v108, v109, v110, v108
	v_max_f32_e32 v109, v93, v93
	v_max_f32_e32 v110, v92, v92
	v_max_f32_e32 v109, v110, v109
	v_max_f32_e32 v110, v95, v95
	v_max_f32_e32 v111, v94, v94
	v_max_f32_e32 v110, v111, v110
	v_max3_f32 v108, v109, v110, v108
	v_max_f32_e32 v109, v89, v89
	v_max_f32_e32 v110, v88, v88
	v_max_f32_e32 v109, v110, v109
	v_max_f32_e32 v110, v91, v91
	v_max_f32_e32 v111, v90, v90
	v_max_f32_e32 v110, v111, v110
	v_max3_f32 v108, v109, v110, v108
	v_max_f32_e32 v109, v85, v85
	v_max_f32_e32 v110, v84, v84
	v_max_f32_e32 v109, v110, v109
	v_max_f32_e32 v110, v87, v87
	v_max_f32_e32 v111, v86, v86
	v_max_f32_e32 v110, v111, v110
	v_max3_f32 v108, v109, v110, v108
	v_max_f32_e32 v109, v81, v81
	v_max_f32_e32 v110, v80, v80
	v_max_f32_e32 v109, v110, v109
	v_max_f32_e32 v110, v83, v83
	v_max_f32_e32 v111, v82, v82
	v_max_f32_e32 v110, v111, v110
	v_max3_f32 v108, v109, v110, v108
	v_max_f32_e32 v109, v77, v77
	v_max_f32_e32 v110, v76, v76
	v_max_f32_e32 v109, v110, v109
	v_max_f32_e32 v110, v79, v79
	v_max_f32_e32 v111, v78, v78
	v_max_f32_e32 v110, v111, v110
	v_max3_f32 v108, v109, v110, v108
	v_max_f32_e32 v109, v73, v73
	v_max_f32_e32 v110, v72, v72
	v_max_f32_e32 v109, v110, v109
	v_max_f32_e32 v110, v75, v75
	v_max_f32_e32 v111, v74, v74
	v_max_f32_e32 v110, v111, v110
	v_max3_f32 v108, v109, v110, v108
	v_max_f32_e32 v109, v69, v69
	v_max_f32_e32 v110, v68, v68
	v_max_f32_e32 v109, v110, v109
	v_max_f32_e32 v110, v71, v71
	v_max_f32_e32 v111, v70, v70
	v_max_f32_e32 v110, v111, v110
	v_max3_f32 v108, v109, v110, v108
	v_max_f32_e32 v109, v65, v65
	v_max_f32_e32 v110, v64, v64
	v_max_f32_e32 v109, v110, v109
	v_max_f32_e32 v110, v67, v67
	v_max_f32_e32 v111, v66, v66
	v_max_f32_e32 v110, v111, v110
	v_max3_f32 v108, v109, v110, v108
	v_max_f32_e32 v109, v45, v45
	v_max_f32_e32 v110, v44, v44
	v_max_f32_e32 v109, v110, v109
	v_max_f32_e32 v110, v47, v47
	v_max_f32_e32 v111, v46, v46
	v_max_f32_e32 v110, v111, v110
	v_max3_f32 v108, v109, v110, v108
	v_max_f32_e32 v109, v49, v49
	v_max_f32_e32 v110, v48, v48
	v_max_f32_e32 v109, v110, v109
	v_max_f32_e32 v110, v51, v51
	v_max_f32_e32 v111, v50, v50
	v_max_f32_e32 v110, v111, v110
	v_max3_f32 v108, v109, v110, v108
	v_max_f32_e32 v109, v53, v53
	v_max_f32_e32 v110, v52, v52
	v_max_f32_e32 v109, v110, v109
	v_max_f32_e32 v110, v55, v55
	v_max_f32_e32 v111, v54, v54
	v_max_f32_e32 v110, v111, v110
	v_max3_f32 v108, v109, v110, v108
	v_max_f32_e32 v109, v57, v57
	v_max_f32_e32 v110, v56, v56
	v_max_f32_e32 v109, v110, v109
	v_max_f32_e32 v110, v59, v59
	v_max_f32_e32 v111, v58, v58
	v_max_f32_e32 v110, v111, v110
	v_max3_f32 v108, v109, v110, v108
	v_max_f32_e32 v109, v61, v61
	v_max_f32_e32 v110, v60, v60
	v_max_f32_e32 v109, v110, v109
	v_max_f32_e32 v110, v63, v63
	v_max_f32_e32 v111, v62, v62
	v_max_f32_e32 v110, v111, v110
	v_max3_f32 v108, v109, v110, v108
	ds_bpermute_b32 v109, v121, v108
	s_waitcnt lgkmcnt(0)
	v_max_f32_e32 v109, v109, v109
	v_max_f32_e32 v108, v108, v109
	ds_bpermute_b32 v109, v122, v108
	s_waitcnt lgkmcnt(0)
	v_max_f32_e32 v109, v109, v109
	v_max_f32_e32 v133, v108, v109
	v_sub_f32_e32 v104, v104, v133
	v_exp_f32_e32 v104, v104
	v_sub_f32_e32 v105, v105, v133
	v_exp_f32_e32 v105, v105
	v_sub_f32_e32 v106, v106, v133
	v_exp_f32_e32 v106, v106
	v_sub_f32_e32 v107, v107, v133
	v_exp_f32_e32 v107, v107
	v_sub_f32_e32 v100, v100, v133
	v_add_f32_e32 v108, 0, v104
	v_exp_f32_e32 v110, v100
	v_sub_f32_e32 v101, v101, v133
	v_add_f32_e32 v108, v105, v108
	v_exp_f32_e32 v130, v101
	v_sub_f32_e32 v101, v102, v133
	v_add_f32_e32 v108, v106, v108
	v_exp_f32_e32 v131, v101
	v_sub_f32_e32 v101, v103, v133
	v_add_f32_e32 v108, v107, v108
	v_exp_f32_e32 v132, v101
	v_sub_f32_e32 v96, v96, v133
	v_add_f32_e32 v100, v110, v108
	v_exp_f32_e32 v96, v96
	v_sub_f32_e32 v97, v97, v133
	v_add_f32_e32 v100, v130, v100
	v_exp_f32_e32 v97, v97
	v_add_f32_e32 v100, v131, v100
	v_add_f32_e32 v100, v132, v100
	v_add_f32_e32 v100, v96, v100
	v_sub_f32_e32 v98, v98, v133
	v_add_f32_e32 v101, v97, v100
	v_exp_f32_e32 v100, v98
	v_sub_f32_e32 v99, v99, v133
	v_sub_f32_e32 v92, v92, v133
	v_exp_f32_e32 v103, v92
	v_add_f32_e32 v98, v100, v101
	v_exp_f32_e32 v101, v99
	v_sub_f32_e32 v93, v93, v133
	v_exp_f32_e32 v111, v93
	v_sub_f32_e32 v93, v94, v133
	v_exp_f32_e32 v113, v93
	v_sub_f32_e32 v93, v95, v133
	v_add_f32_e32 v98, v101, v98
	v_exp_f32_e32 v129, v93
	v_sub_f32_e32 v88, v88, v133
	v_add_f32_e32 v92, v103, v98
	v_exp_f32_e32 v88, v88
	v_sub_f32_e32 v89, v89, v133
	v_add_f32_e32 v92, v111, v92
	v_exp_f32_e32 v89, v89
	v_add_f32_e32 v92, v113, v92
	v_add_f32_e32 v92, v129, v92
	v_add_f32_e32 v92, v88, v92
	v_sub_f32_e32 v90, v90, v133
	v_add_f32_e32 v93, v89, v92
	v_exp_f32_e32 v92, v90
	v_sub_f32_e32 v91, v91, v133
	v_sub_f32_e32 v84, v84, v133
	v_exp_f32_e32 v95, v84
	v_add_f32_e32 v90, v92, v93
	v_exp_f32_e32 v93, v91
	v_sub_f32_e32 v85, v85, v133
	v_exp_f32_e32 v102, v85
	v_sub_f32_e32 v85, v86, v133
	v_exp_f32_e32 v108, v85
	v_sub_f32_e32 v85, v87, v133
	v_add_f32_e32 v90, v93, v90
	v_exp_f32_e32 v109, v85
	v_sub_f32_e32 v80, v80, v133
	v_add_f32_e32 v84, v95, v90
	v_exp_f32_e32 v80, v80
	v_sub_f32_e32 v81, v81, v133
	v_add_f32_e32 v84, v102, v84
	v_exp_f32_e32 v81, v81
	v_add_f32_e32 v84, v108, v84
	v_add_f32_e32 v84, v109, v84
	v_add_f32_e32 v84, v80, v84
	v_sub_f32_e32 v82, v82, v133
	v_add_f32_e32 v85, v81, v84
	v_exp_f32_e32 v84, v82
	v_sub_f32_e32 v83, v83, v133
	v_sub_f32_e32 v76, v76, v133
	v_exp_f32_e32 v87, v76
	v_add_f32_e32 v82, v84, v85
	v_exp_f32_e32 v85, v83
	v_sub_f32_e32 v77, v77, v133
	v_exp_f32_e32 v94, v77
	v_sub_f32_e32 v77, v78, v133
	v_exp_f32_e32 v98, v77
	v_sub_f32_e32 v77, v79, v133
	v_add_f32_e32 v82, v85, v82
	v_exp_f32_e32 v99, v77
	v_sub_f32_e32 v72, v72, v133
	v_add_f32_e32 v76, v87, v82
	v_exp_f32_e32 v72, v72
	v_add_f32_e32 v76, v94, v76
	v_add_f32_e32 v76, v98, v76
	v_add_f32_e32 v76, v99, v76
	v_sub_f32_e32 v73, v73, v133
	v_add_f32_e32 v77, v72, v76
	v_exp_f32_e32 v76, v73
	v_sub_f32_e32 v74, v74, v133
	v_sub_f32_e32 v68, v68, v133
	v_exp_f32_e32 v79, v68
	v_add_f32_e32 v73, v76, v77
	v_exp_f32_e32 v77, v74
	v_sub_f32_e32 v74, v75, v133
	v_exp_f32_e32 v75, v74
	v_sub_f32_e32 v69, v69, v133
	v_exp_f32_e32 v86, v69
	v_sub_f32_e32 v69, v70, v133
	v_add_f32_e32 v73, v77, v73
	v_exp_f32_e32 v90, v69
	v_sub_f32_e32 v69, v71, v133
	v_add_f32_e32 v73, v75, v73
	v_exp_f32_e32 v91, v69
	v_sub_f32_e32 v64, v64, v133
	v_add_f32_e32 v68, v79, v73
	v_exp_f32_e32 v69, v64
	v_sub_f32_e32 v65, v65, v133
	v_add_f32_e32 v68, v86, v68
	v_exp_f32_e32 v70, v65
	v_sub_f32_e32 v65, v66, v133
	v_add_f32_e32 v68, v90, v68
	v_exp_f32_e32 v71, v65
	v_sub_f32_e32 v65, v67, v133
	v_add_f32_e32 v68, v91, v68
	v_exp_f32_e32 v73, v65
	v_sub_f32_e32 v44, v44, v133
	v_add_f32_e32 v64, v69, v68
	v_exp_f32_e32 v74, v44
	v_sub_f32_e32 v45, v45, v133
	v_add_f32_e32 v64, v70, v64
	v_exp_f32_e32 v78, v45
	v_sub_f32_e32 v45, v46, v133
	v_add_f32_e32 v64, v71, v64
	v_exp_f32_e32 v82, v45
	v_sub_f32_e32 v45, v47, v133
	v_add_f32_e32 v64, v73, v64
	v_exp_f32_e32 v83, v45
	v_sub_f32_e32 v45, v48, v133
	v_add_f32_e32 v44, v74, v64
	v_exp_f32_e32 v64, v45
	v_sub_f32_e32 v45, v49, v133
	v_add_f32_e32 v44, v78, v44
	v_exp_f32_e32 v65, v45
	v_sub_f32_e32 v45, v50, v133
	v_add_f32_e32 v44, v82, v44
	v_exp_f32_e32 v66, v45
	v_sub_f32_e32 v45, v51, v133
	v_add_f32_e32 v44, v83, v44
	v_exp_f32_e32 v67, v45
	v_sub_f32_e32 v45, v52, v133
	v_add_f32_e32 v44, v64, v44
	v_exp_f32_e32 v68, v45
	v_sub_f32_e32 v45, v53, v133
	v_add_f32_e32 v44, v65, v44
	v_exp_f32_e32 v53, v45
	v_sub_f32_e32 v45, v54, v133
	v_add_f32_e32 v44, v66, v44
	v_exp_f32_e32 v54, v45
	v_sub_f32_e32 v45, v55, v133
	v_add_f32_e32 v44, v67, v44
	v_exp_f32_e32 v55, v45
	v_sub_f32_e32 v45, v56, v133
	v_add_f32_e32 v44, v68, v44
	v_exp_f32_e32 v45, v45
	v_sub_f32_e32 v46, v57, v133
	v_add_f32_e32 v44, v53, v44
	v_exp_f32_e32 v46, v46
	v_sub_f32_e32 v47, v58, v133
	v_add_f32_e32 v44, v54, v44
	v_exp_f32_e32 v47, v47
	v_sub_f32_e32 v48, v59, v133
	v_add_f32_e32 v44, v55, v44
	v_exp_f32_e32 v48, v48
	v_sub_f32_e32 v49, v60, v133
	v_add_f32_e32 v44, v45, v44
	v_exp_f32_e32 v49, v49
	v_sub_f32_e32 v50, v61, v133
	v_add_f32_e32 v44, v46, v44
	v_exp_f32_e32 v50, v50
	v_sub_f32_e32 v51, v62, v133
	v_add_f32_e32 v44, v47, v44
	v_exp_f32_e32 v51, v51
	v_sub_f32_e32 v52, v63, v133
	v_add_f32_e32 v44, v48, v44
	v_exp_f32_e32 v52, v52
	v_add_f32_e32 v44, v49, v44
	v_add_f32_e32 v44, v50, v44
	v_add_f32_e32 v44, v51, v44
	v_add_f32_e32 v44, v52, v44
	ds_bpermute_b32 v56, v121, v44
	s_waitcnt lgkmcnt(0)
	v_add_f32_e32 v44, v44, v56
	ds_bpermute_b32 v56, v122, v44
	s_waitcnt lgkmcnt(0)
	v_add_f32_e32 v44, v44, v56
	v_cvt_pk_bf16_f32 v56, v104, v105
	v_cvt_pk_bf16_f32 v57, v106, v107
	v_add_u32_e32 v105, 0x9000, v124
	v_add_u32_e32 v104, 0x9000, v125
	v_add_u32_e32 v107, 0x9000, v126
	v_add_u32_e32 v106, 0x9000, v127
	v_cvt_pk_bf16_f32 v58, v110, v130
	v_cvt_pk_bf16_f32 v59, v131, v132
	ds_read2_b64 v[60:63], v105 offset1:4
	ds_read2_b64 v[130:133], v104 offset1:4
	ds_read2_b64 v[134:137], v107 offset1:4
	ds_read2_b64 v[138:141], v106 offset1:4
	s_waitcnt lgkmcnt(3)
	v_mfma_f32_16x16x32_bf16 v[60:63], v[60:63], v[56:59], 0
	s_waitcnt lgkmcnt(2)
	v_mfma_f32_16x16x32_bf16 v[130:133], v[130:133], v[56:59], 0
	s_waitcnt lgkmcnt(1)
	v_mfma_f32_16x16x32_bf16 v[134:137], v[134:137], v[56:59], 0
	s_waitcnt lgkmcnt(0)
	v_mfma_f32_16x16x32_bf16 v[56:59], v[138:141], v[56:59], 0
	v_cvt_pk_bf16_f32 v138, v96, v97
	v_cvt_pk_bf16_f32 v139, v100, v101
	v_cvt_pk_bf16_f32 v140, v103, v111
	v_cvt_pk_bf16_f32 v141, v113, v129
	ds_read2_b64 v[142:145], v105 offset0:8 offset1:12
	s_waitcnt lgkmcnt(0)
	v_mfma_f32_16x16x32_bf16 v[60:63], v[142:145], v[138:141], v[60:63]
	ds_read2_b64 v[142:145], v104 offset0:8 offset1:12
	s_waitcnt lgkmcnt(0)
	v_mfma_f32_16x16x32_bf16 v[130:133], v[142:145], v[138:141], v[130:133]
	ds_read2_b64 v[142:145], v107 offset0:8 offset1:12
	s_waitcnt lgkmcnt(0)
	v_mfma_f32_16x16x32_bf16 v[134:137], v[142:145], v[138:141], v[134:137]
	ds_read2_b64 v[142:145], v106 offset0:8 offset1:12
	v_cvt_pk_bf16_f32 v100, v88, v89
	v_cvt_pk_bf16_f32 v101, v92, v93
	v_cvt_pk_bf16_f32 v102, v95, v102
	v_cvt_pk_bf16_f32 v103, v108, v109
	ds_read2_b64 v[108:111], v105 offset0:16 offset1:20
	s_waitcnt lgkmcnt(0)
	v_mfma_f32_16x16x32_bf16 v[60:63], v[108:111], v[100:103], v[60:63]
	ds_read2_b64 v[108:111], v104 offset0:16 offset1:20
	s_waitcnt lgkmcnt(0)
	v_mfma_f32_16x16x32_bf16 v[108:111], v[108:111], v[100:103], v[130:133]
	s_nop 2
	ds_read2_b64 v[130:133], v107 offset0:16 offset1:20
	s_waitcnt lgkmcnt(0)
	v_mfma_f32_16x16x32_bf16 v[130:133], v[130:133], v[100:103], v[134:137]
	s_nop 2
	ds_read2_b64 v[134:137], v106 offset0:16 offset1:20
	v_cvt_pk_bf16_f32 v92, v80, v81
	v_cvt_pk_bf16_f32 v93, v84, v85
	v_cvt_pk_bf16_f32 v94, v87, v94
	v_cvt_pk_bf16_f32 v95, v98, v99
	ds_read2_b64 v[96:99], v105 offset0:24 offset1:28
	s_waitcnt lgkmcnt(0)
	v_mfma_f32_16x16x32_bf16 v[60:63], v[96:99], v[92:95], v[60:63]
	ds_read2_b64 v[96:99], v104 offset0:24 offset1:28
	v_mfma_f32_16x16x32_bf16 v[56:59], v[142:145], v[138:141], v[56:59]
	v_mfma_f32_16x16x32_bf16 v[56:59], v[134:137], v[100:103], v[56:59]
	ds_read2_b64 v[100:103], v107 offset0:24 offset1:28
	s_waitcnt lgkmcnt(1)
	v_mfma_f32_16x16x32_bf16 v[96:99], v[96:99], v[92:95], v[108:111]
	s_nop 2
	ds_read2_b64 v[108:111], v106 offset0:24 offset1:28
	v_cvt_pk_bf16_f32 v84, v72, v76
	v_cvt_pk_bf16_f32 v85, v77, v75
	v_cvt_pk_bf16_f32 v86, v79, v86
	v_cvt_pk_bf16_f32 v87, v90, v91
	ds_read2_b64 v[88:91], v105 offset0:32 offset1:36
	s_waitcnt lgkmcnt(0)
	v_mfma_f32_16x16x32_bf16 v[60:63], v[88:91], v[84:87], v[60:63]
	ds_read2_b64 v[88:91], v104 offset0:32 offset1:36
	v_mfma_f32_16x16x32_bf16 v[100:103], v[100:103], v[92:95], v[130:133]
	v_mfma_f32_16x16x32_bf16 v[56:59], v[108:111], v[92:95], v[56:59]
	ds_read2_b64 v[92:95], v107 offset0:32 offset1:36
	s_waitcnt lgkmcnt(1)
	v_mfma_f32_16x16x32_bf16 v[88:91], v[88:91], v[84:87], v[96:99]
	s_nop 2
	ds_read2_b64 v[96:99], v106 offset0:32 offset1:36
	v_cvt_pk_bf16_f32 v70, v69, v70
	v_cvt_pk_bf16_f32 v71, v71, v73
	v_cvt_pk_bf16_f32 v72, v74, v78
	v_cvt_pk_bf16_f32 v73, v82, v83
	ds_read2_b64 v[74:77], v105 offset0:40 offset1:44
	s_waitcnt lgkmcnt(2)
	v_mfma_f32_16x16x32_bf16 v[92:95], v[92:95], v[84:87], v[100:103]
	ds_read2_b64 v[78:81], v107 offset0:40 offset1:44
	s_waitcnt lgkmcnt(2)
	v_mfma_f32_16x16x32_bf16 v[56:59], v[96:99], v[84:87], v[56:59]
	ds_read2_b64 v[82:85], v106 offset0:40 offset1:44
	s_waitcnt lgkmcnt(2)
	v_mfma_f32_16x16x32_bf16 v[60:63], v[74:77], v[70:73], v[60:63]
	ds_read2_b64 v[74:77], v104 offset0:40 offset1:44
	v_cvt_pk_bf16_f32 v64, v64, v65
	v_cvt_pk_bf16_f32 v65, v66, v67
	s_waitcnt lgkmcnt(0)
	v_mfma_f32_16x16x32_bf16 v[74:77], v[74:77], v[70:73], v[88:91]
	v_cvt_pk_bf16_f32 v66, v68, v53
	v_cvt_pk_bf16_f32 v67, v54, v55
	v_mfma_f32_16x16x32_bf16 v[78:81], v[78:81], v[70:73], v[92:95]
	v_mfma_f32_16x16x32_bf16 v[56:59], v[82:85], v[70:73], v[56:59]
	ds_read2_b64 v[68:71], v105 offset0:48 offset1:52
	s_waitcnt lgkmcnt(0)
	v_mfma_f32_16x16x32_bf16 v[60:63], v[68:71], v[64:67], v[60:63]
	ds_read2_b64 v[68:71], v104 offset0:48 offset1:52
	s_waitcnt lgkmcnt(0)
	v_mfma_f32_16x16x32_bf16 v[68:71], v[68:71], v[64:67], v[74:77]
	s_nop 2
	ds_read2_b64 v[72:75], v107 offset0:48 offset1:52
	s_waitcnt lgkmcnt(0)
	v_mfma_f32_16x16x32_bf16 v[72:75], v[72:75], v[64:67], v[78:81]
	s_nop 2
	ds_read2_b64 v[76:79], v106 offset0:48 offset1:52
	v_cvt_pk_bf16_f32 v46, v45, v46
	v_cvt_pk_bf16_f32 v47, v47, v48
	v_cvt_pk_bf16_f32 v48, v49, v50
	v_cvt_pk_bf16_f32 v49, v51, v52
	ds_read2_b64 v[50:53], v105 offset0:56 offset1:60
	s_waitcnt lgkmcnt(1)
	v_mfma_f32_16x16x32_bf16 v[54:57], v[76:79], v[64:67], v[56:59]
	v_div_scale_f32 v45, s[10:11], v44, v44, 1.0
	s_waitcnt lgkmcnt(0)
	v_mfma_f32_16x16x32_bf16 v[50:53], v[50:53], v[46:49], v[60:63]
	s_nop 2
	ds_read2_b64 v[58:61], v104 offset0:56 offset1:60
	s_waitcnt lgkmcnt(0)
	v_mfma_f32_16x16x32_bf16 v[58:61], v[58:61], v[46:49], v[68:71]
	ds_read2_b64 v[62:65], v107 offset0:56 offset1:60
	s_nop 1
	ds_read2_b64 v[66:69], v106 offset0:56 offset1:60
	s_waitcnt lgkmcnt(1)
	v_mfma_f32_16x16x32_bf16 v[62:65], v[62:65], v[46:49], v[72:75]
	s_waitcnt lgkmcnt(0)
	v_mfma_f32_16x16x32_bf16 v[46:49], v[66:69], v[46:49], v[54:57]
	s_nop 2
	v_rcp_f32_e32 v54, v45
	s_nop 0
	v_fma_f32 v55, -v45, v54, 1.0
	v_fmac_f32_e32 v54, v55, v54
	v_div_scale_f32 v55, vcc, 1.0, v44, 1.0
	v_mul_f32_e32 v56, v55, v54
	v_fma_f32 v57, -v45, v56, v55
	v_fmac_f32_e32 v56, v57, v54
	v_fma_f32 v45, -v45, v56, v55
	v_div_fmas_f32 v45, v45, v54, v56
	v_div_fixup_f32 v54, v45, v44, 1.0
	v_lshlrev_b64 v[44:45], 11, v[116:117]
	v_lshl_add_u64 v[44:45], s[4:5], 0, v[44:45]
	v_mul_f32_e32 v50, v54, v50
	v_mul_f32_e32 v51, v54, v51
	v_lshl_add_u64 v[44:45], v[44:45], 0, s[36:37]
	v_cvt_pk_bf16_f32 v50, v50, v51
	v_mul_f32_e32 v51, v54, v52
	v_lshl_add_u64 v[44:45], v[44:45], 0, v[2:3]
	v_mul_f32_e32 v52, v54, v53
	v_cvt_pk_bf16_f32 v51, v51, v52
	global_store_dwordx2 v[44:45], v[50:51], off offset:1536
	v_mul_f32_e32 v50, v54, v58
	v_mul_f32_e32 v51, v54, v59
	v_cvt_pk_bf16_f32 v50, v50, v51
	v_mul_f32_e32 v51, v54, v60
	v_mul_f32_e32 v52, v54, v61
	v_cvt_pk_bf16_f32 v51, v51, v52
	global_store_dwordx2 v[44:45], v[50:51], off offset:1568
	v_mul_f32_e32 v50, v54, v62
	v_mul_f32_e32 v51, v54, v63
	v_cvt_pk_bf16_f32 v50, v50, v51
	v_mul_f32_e32 v51, v54, v64
	v_mul_f32_e32 v46, v54, v46
	v_mul_f32_e32 v47, v54, v47
	v_mul_f32_e32 v52, v54, v65
	v_cvt_pk_bf16_f32 v51, v51, v52
	global_store_dwordx2 v[44:45], v[50:51], off offset:1600
	v_cvt_pk_bf16_f32 v46, v46, v47
	v_mul_f32_e32 v47, v54, v48
	v_mul_f32_e32 v48, v54, v49
	v_cvt_pk_bf16_f32 v47, v47, v48
	global_store_dwordx2 v[44:45], v[46:47], off offset:1632
	ds_read_b128 v[44:47], v128
	ds_read_b128 v[48:51], v128 offset:64
	s_waitcnt vmcnt(13) lgkmcnt(1)
	v_mfma_f32_16x16x32_bf16 v[44:47], v[44:47], v[40:43], 0
	ds_read_b128 v[52:55], v128 offset:27712
	ds_read_b128 v[56:59], v128 offset:30016
	ds_read_b128 v[108:111], v128 offset:32320
	s_waitcnt vmcnt(12) lgkmcnt(3)
	v_mfma_f32_16x16x32_bf16 v[100:103], v[48:51], v[36:39], v[44:47]
	ds_read_b128 v[48:51], v128 offset:2368
	s_nop 1
	ds_read_b128 v[44:47], v128 offset:2304
	s_waitcnt lgkmcnt(0)
	v_mfma_f32_16x16x32_bf16 v[44:47], v[44:47], v[40:43], 0
	v_mfma_f32_16x16x32_bf16 v[96:99], v[48:51], v[36:39], v[44:47]
	ds_read_b128 v[48:51], v128 offset:4672
	s_nop 5
	ds_read_b128 v[44:47], v128 offset:4608
	s_waitcnt lgkmcnt(0)
	v_mfma_f32_16x16x32_bf16 v[44:47], v[44:47], v[40:43], 0
	v_mfma_f32_16x16x32_bf16 v[92:95], v[48:51], v[36:39], v[44:47]
	ds_read_b128 v[48:51], v128 offset:6976
	s_nop 5
	ds_read_b128 v[44:47], v128 offset:6912
	s_waitcnt lgkmcnt(0)
	v_mfma_f32_16x16x32_bf16 v[44:47], v[44:47], v[40:43], 0
	v_mfma_f32_16x16x32_bf16 v[88:91], v[48:51], v[36:39], v[44:47]
	ds_read_b128 v[48:51], v128 offset:9280
	s_nop 5
	ds_read_b128 v[44:47], v128 offset:9216
	s_waitcnt lgkmcnt(0)
	v_mfma_f32_16x16x32_bf16 v[44:47], v[44:47], v[40:43], 0
	v_mfma_f32_16x16x32_bf16 v[84:87], v[48:51], v[36:39], v[44:47]
	ds_read_b128 v[48:51], v128 offset:11584
	s_nop 5
	ds_read_b128 v[44:47], v128 offset:11520
	s_waitcnt lgkmcnt(0)
	v_mfma_f32_16x16x32_bf16 v[44:47], v[44:47], v[40:43], 0
	v_mfma_f32_16x16x32_bf16 v[80:83], v[48:51], v[36:39], v[44:47]
	ds_read_b128 v[48:51], v128 offset:13888
	s_nop 5
	ds_read_b128 v[44:47], v128 offset:13824
	s_waitcnt lgkmcnt(0)
	v_mfma_f32_16x16x32_bf16 v[44:47], v[44:47], v[40:43], 0
	v_mfma_f32_16x16x32_bf16 v[76:79], v[48:51], v[36:39], v[44:47]
	ds_read_b128 v[48:51], v128 offset:16192
	s_nop 5
	ds_read_b128 v[44:47], v128 offset:16128
	s_waitcnt lgkmcnt(0)
	v_mfma_f32_16x16x32_bf16 v[44:47], v[44:47], v[40:43], 0
	v_mfma_f32_16x16x32_bf16 v[72:75], v[48:51], v[36:39], v[44:47]
	ds_read_b128 v[48:51], v128 offset:18496
	s_nop 5
	ds_read_b128 v[44:47], v128 offset:18432
	s_waitcnt lgkmcnt(0)
	v_mfma_f32_16x16x32_bf16 v[44:47], v[44:47], v[40:43], 0
	v_mfma_f32_16x16x32_bf16 v[68:71], v[48:51], v[36:39], v[44:47]
	ds_read_b128 v[48:51], v128 offset:20800
	s_nop 5
	ds_read_b128 v[44:47], v128 offset:20736
	s_waitcnt lgkmcnt(0)
	v_mfma_f32_16x16x32_bf16 v[44:47], v[44:47], v[40:43], 0
	v_mfma_f32_16x16x32_bf16 v[64:67], v[48:51], v[36:39], v[44:47]
	ds_read_b128 v[48:51], v128 offset:23104
	s_nop 5
	ds_read_b128 v[44:47], v128 offset:23040
	s_waitcnt lgkmcnt(0)
	v_mfma_f32_16x16x32_bf16 v[44:47], v[44:47], v[40:43], 0
	v_mfma_f32_16x16x32_bf16 v[60:63], v[48:51], v[36:39], v[44:47]
	ds_read_b128 v[48:51], v128 offset:25408
	s_nop 5
	ds_read_b128 v[44:47], v128 offset:25344
	s_waitcnt lgkmcnt(0)
	v_mfma_f32_16x16x32_bf16 v[44:47], v[44:47], v[40:43], 0
	v_mfma_f32_16x16x32_bf16 v[44:47], v[48:51], v[36:39], v[44:47]
	ds_read_b128 v[48:51], v128 offset:27648
	s_waitcnt lgkmcnt(0)
	v_mfma_f32_16x16x32_bf16 v[48:51], v[48:51], v[40:43], 0
	v_mfma_f32_16x16x32_bf16 v[48:51], v[52:55], v[36:39], v[48:51]
	ds_read_b128 v[52:55], v128 offset:29952
	s_waitcnt lgkmcnt(0)
	v_mfma_f32_16x16x32_bf16 v[52:55], v[52:55], v[40:43], 0
	v_mfma_f32_16x16x32_bf16 v[52:55], v[56:59], v[36:39], v[52:55]
	ds_read_b128 v[56:59], v128 offset:32256
	s_waitcnt lgkmcnt(0)
	v_mfma_f32_16x16x32_bf16 v[56:59], v[56:59], v[40:43], 0
	v_mfma_f32_16x16x32_bf16 v[56:59], v[108:111], v[36:39], v[56:59]
	ds_read_b128 v[108:111], v128 offset:34560
	s_waitcnt lgkmcnt(0)
	v_mfma_f32_16x16x32_bf16 v[40:43], v[108:111], v[40:43], 0
	ds_read_b128 v[108:111], v128 offset:34624
	s_waitcnt lgkmcnt(0)
	v_mfma_f32_16x16x32_bf16 v[36:39], v[108:111], v[36:39], v[40:43]
	s_nop 4
	v_max_f32_e32 v40, v101, v101
	v_max_f32_e32 v41, v100, v100
	v_max_f32_e32 v40, v41, v40
	v_max_f32_e32 v41, v103, v103
	v_max_f32_e32 v42, v102, v102
	v_max_f32_e32 v41, v42, v41
	v_max3_f32 v40, v40, v41, s9
	v_max_f32_e32 v41, v97, v97
	v_max_f32_e32 v42, v96, v96
	v_max_f32_e32 v41, v42, v41
	v_max_f32_e32 v42, v99, v99
	v_max_f32_e32 v43, v98, v98
	v_max_f32_e32 v42, v43, v42
	v_max3_f32 v40, v41, v42, v40
	v_max_f32_e32 v41, v93, v93
	v_max_f32_e32 v42, v92, v92
	v_max_f32_e32 v41, v42, v41
	v_max_f32_e32 v42, v95, v95
	v_max_f32_e32 v43, v94, v94
	v_max_f32_e32 v42, v43, v42
	v_max3_f32 v40, v41, v42, v40
	v_max_f32_e32 v41, v89, v89
	v_max_f32_e32 v42, v88, v88
	v_max_f32_e32 v41, v42, v41
	v_max_f32_e32 v42, v91, v91
	v_max_f32_e32 v43, v90, v90
	v_max_f32_e32 v42, v43, v42
	v_max3_f32 v40, v41, v42, v40
	v_max_f32_e32 v41, v85, v85
	v_max_f32_e32 v42, v84, v84
	v_max_f32_e32 v41, v42, v41
	v_max_f32_e32 v42, v87, v87
	v_max_f32_e32 v43, v86, v86
	v_max_f32_e32 v42, v43, v42
	v_max3_f32 v40, v41, v42, v40
	v_max_f32_e32 v41, v81, v81
	v_max_f32_e32 v42, v80, v80
	v_max_f32_e32 v41, v42, v41
	v_max_f32_e32 v42, v83, v83
	v_max_f32_e32 v43, v82, v82
	v_max_f32_e32 v42, v43, v42
	v_max3_f32 v40, v41, v42, v40
	v_max_f32_e32 v41, v77, v77
	v_max_f32_e32 v42, v76, v76
	v_max_f32_e32 v41, v42, v41
	v_max_f32_e32 v42, v79, v79
	v_max_f32_e32 v43, v78, v78
	v_max_f32_e32 v42, v43, v42
	v_max3_f32 v40, v41, v42, v40
	v_max_f32_e32 v41, v73, v73
	v_max_f32_e32 v42, v72, v72
	v_max_f32_e32 v41, v42, v41
	v_max_f32_e32 v42, v75, v75
	v_max_f32_e32 v43, v74, v74
	v_max_f32_e32 v42, v43, v42
	v_max3_f32 v40, v41, v42, v40
	v_max_f32_e32 v41, v69, v69
	v_max_f32_e32 v42, v68, v68
	v_max_f32_e32 v41, v42, v41
	v_max_f32_e32 v42, v71, v71
	v_max_f32_e32 v43, v70, v70
	v_max_f32_e32 v42, v43, v42
	v_max3_f32 v40, v41, v42, v40
	v_max_f32_e32 v41, v65, v65
	v_max_f32_e32 v42, v64, v64
	v_max_f32_e32 v41, v42, v41
	v_max_f32_e32 v42, v67, v67
	v_max_f32_e32 v43, v66, v66
	v_max_f32_e32 v42, v43, v42
	v_max3_f32 v40, v41, v42, v40
	v_max_f32_e32 v41, v61, v61
	v_max_f32_e32 v42, v60, v60
	v_max_f32_e32 v41, v42, v41
	v_max_f32_e32 v42, v63, v63
	v_max_f32_e32 v43, v62, v62
	v_max_f32_e32 v42, v43, v42
	v_max3_f32 v40, v41, v42, v40
	v_max_f32_e32 v41, v45, v45
	v_max_f32_e32 v42, v44, v44
	v_max_f32_e32 v41, v42, v41
	v_max_f32_e32 v42, v47, v47
	v_max_f32_e32 v43, v46, v46
	v_max_f32_e32 v42, v43, v42
	v_max3_f32 v40, v41, v42, v40
	v_max_f32_e32 v41, v49, v49
	v_max_f32_e32 v42, v48, v48
	v_max_f32_e32 v41, v42, v41
	v_max_f32_e32 v42, v51, v51
	v_max_f32_e32 v43, v50, v50
	v_max_f32_e32 v42, v43, v42
	v_max3_f32 v40, v41, v42, v40
	v_max_f32_e32 v41, v53, v53
	v_max_f32_e32 v42, v52, v52
	v_max_f32_e32 v41, v42, v41
	v_max_f32_e32 v42, v55, v55
	v_max_f32_e32 v43, v54, v54
	v_max_f32_e32 v42, v43, v42
	v_max3_f32 v40, v41, v42, v40
	v_max_f32_e32 v41, v57, v57
	v_max_f32_e32 v42, v56, v56
	v_max_f32_e32 v41, v42, v41
	v_max_f32_e32 v42, v59, v59
	v_max_f32_e32 v43, v58, v58
	v_max_f32_e32 v42, v43, v42
	v_max3_f32 v40, v41, v42, v40
	v_max_f32_e32 v41, v37, v37
	v_max_f32_e32 v42, v36, v36
	v_max_f32_e32 v41, v42, v41
	v_max_f32_e32 v42, v39, v39
	v_max_f32_e32 v43, v38, v38
	v_max_f32_e32 v42, v43, v42
	v_max3_f32 v40, v41, v42, v40
	ds_bpermute_b32 v41, v121, v40
	v_readlane_b32 s9, v243, 34
	s_add_i32 s8, s8, s9
	v_readlane_b32 s9, v243, 38
	s_add_i32 s7, s7, s9
	s_waitcnt lgkmcnt(0)
	v_max_f32_e32 v41, v41, v41
	v_max_f32_e32 v40, v40, v41
	ds_bpermute_b32 v41, v122, v40
	v_readlane_b32 s9, v244, 11
	s_add_i32 s6, s6, s9
	s_cmpk_lt_i32 s6, 0x200
	s_waitcnt lgkmcnt(0)
	v_max_f32_e32 v41, v41, v41
	v_max_f32_e32 v113, v40, v41
	v_sub_f32_e32 v40, v100, v113
	v_exp_f32_e32 v100, v40
	v_sub_f32_e32 v41, v101, v113
	v_exp_f32_e32 v101, v41
	v_sub_f32_e32 v41, v102, v113
	v_exp_f32_e32 v102, v41
	v_sub_f32_e32 v41, v103, v113
	v_exp_f32_e32 v103, v41
	v_sub_f32_e32 v41, v96, v113
	v_add_f32_e32 v40, 0, v100
	v_exp_f32_e32 v108, v41
	v_sub_f32_e32 v41, v97, v113
	v_add_f32_e32 v40, v101, v40
	v_exp_f32_e32 v109, v41
	v_sub_f32_e32 v41, v98, v113
	v_add_f32_e32 v40, v102, v40
	v_exp_f32_e32 v110, v41
	v_sub_f32_e32 v41, v99, v113
	v_add_f32_e32 v40, v103, v40
	v_exp_f32_e32 v111, v41
	v_sub_f32_e32 v41, v92, v113
	v_add_f32_e32 v40, v108, v40
	v_exp_f32_e32 v92, v41
	v_sub_f32_e32 v41, v93, v113
	v_add_f32_e32 v40, v109, v40
	v_exp_f32_e32 v93, v41
	v_sub_f32_e32 v41, v94, v113
	v_add_f32_e32 v40, v110, v40
	v_exp_f32_e32 v94, v41
	v_sub_f32_e32 v41, v95, v113
	v_add_f32_e32 v40, v111, v40
	v_exp_f32_e32 v95, v41
	v_sub_f32_e32 v41, v88, v113
	v_add_f32_e32 v40, v92, v40
	v_exp_f32_e32 v96, v41
	v_sub_f32_e32 v41, v89, v113
	v_add_f32_e32 v40, v93, v40
	v_exp_f32_e32 v97, v41
	v_sub_f32_e32 v41, v90, v113
	v_add_f32_e32 v40, v94, v40
	v_exp_f32_e32 v98, v41
	v_sub_f32_e32 v41, v91, v113
	v_add_f32_e32 v40, v95, v40
	v_exp_f32_e32 v99, v41
	v_sub_f32_e32 v41, v84, v113
	v_add_f32_e32 v40, v96, v40
	v_exp_f32_e32 v84, v41
	v_sub_f32_e32 v41, v85, v113
	v_add_f32_e32 v40, v97, v40
	v_exp_f32_e32 v85, v41
	v_sub_f32_e32 v41, v86, v113
	v_add_f32_e32 v40, v98, v40
	v_exp_f32_e32 v86, v41
	v_sub_f32_e32 v41, v87, v113
	v_add_f32_e32 v40, v99, v40
	v_exp_f32_e32 v87, v41
	v_sub_f32_e32 v41, v80, v113
	v_add_f32_e32 v40, v84, v40
	v_exp_f32_e32 v88, v41
	v_sub_f32_e32 v41, v81, v113
	v_add_f32_e32 v40, v85, v40
	v_exp_f32_e32 v89, v41
	v_sub_f32_e32 v41, v82, v113
	v_add_f32_e32 v40, v86, v40
	v_exp_f32_e32 v90, v41
	v_sub_f32_e32 v41, v83, v113
	v_add_f32_e32 v40, v87, v40
	v_exp_f32_e32 v91, v41
	v_sub_f32_e32 v41, v76, v113
	v_add_f32_e32 v40, v88, v40
	v_exp_f32_e32 v76, v41
	v_sub_f32_e32 v41, v77, v113
	v_add_f32_e32 v40, v89, v40
	v_exp_f32_e32 v77, v41
	v_sub_f32_e32 v41, v78, v113
	v_add_f32_e32 v40, v90, v40
	v_exp_f32_e32 v78, v41
	v_sub_f32_e32 v41, v79, v113
	v_add_f32_e32 v40, v91, v40
	v_exp_f32_e32 v79, v41
	v_sub_f32_e32 v41, v72, v113
	v_add_f32_e32 v40, v76, v40
	v_exp_f32_e32 v80, v41
	v_sub_f32_e32 v41, v73, v113
	v_add_f32_e32 v40, v77, v40
	v_exp_f32_e32 v81, v41
	v_sub_f32_e32 v41, v74, v113
	v_add_f32_e32 v40, v78, v40
	v_exp_f32_e32 v82, v41
	v_sub_f32_e32 v41, v75, v113
	v_add_f32_e32 v40, v79, v40
	v_exp_f32_e32 v83, v41
	v_sub_f32_e32 v41, v68, v113
	v_add_f32_e32 v40, v80, v40
	v_exp_f32_e32 v68, v41
	v_sub_f32_e32 v41, v69, v113
	v_add_f32_e32 v40, v81, v40
	v_exp_f32_e32 v69, v41
	v_sub_f32_e32 v41, v70, v113
	v_add_f32_e32 v40, v82, v40
	v_exp_f32_e32 v70, v41
	v_sub_f32_e32 v41, v71, v113
	v_add_f32_e32 v40, v83, v40
	v_exp_f32_e32 v71, v41
	v_sub_f32_e32 v41, v64, v113
	v_add_f32_e32 v40, v68, v40
	v_exp_f32_e32 v72, v41
	v_sub_f32_e32 v41, v65, v113
	v_add_f32_e32 v40, v69, v40
	v_exp_f32_e32 v73, v41
	v_sub_f32_e32 v41, v66, v113
	v_add_f32_e32 v40, v70, v40
	v_exp_f32_e32 v74, v41
	v_sub_f32_e32 v41, v67, v113
	v_add_f32_e32 v40, v71, v40
	v_exp_f32_e32 v75, v41
	v_sub_f32_e32 v41, v60, v113
	v_add_f32_e32 v40, v72, v40
	v_exp_f32_e32 v60, v41
	v_sub_f32_e32 v41, v61, v113
	v_add_f32_e32 v40, v73, v40
	v_exp_f32_e32 v61, v41
	v_sub_f32_e32 v41, v62, v113
	v_add_f32_e32 v40, v74, v40
	v_exp_f32_e32 v62, v41
	v_sub_f32_e32 v41, v63, v113
	v_add_f32_e32 v40, v75, v40
	v_exp_f32_e32 v63, v41
	v_sub_f32_e32 v41, v44, v113
	v_add_f32_e32 v40, v60, v40
	v_exp_f32_e32 v64, v41
	v_sub_f32_e32 v41, v45, v113
	v_add_f32_e32 v40, v61, v40
	v_exp_f32_e32 v65, v41
	v_sub_f32_e32 v41, v46, v113
	v_add_f32_e32 v40, v62, v40
	v_exp_f32_e32 v66, v41
	v_sub_f32_e32 v41, v47, v113
	v_add_f32_e32 v40, v63, v40
	v_exp_f32_e32 v67, v41
	v_sub_f32_e32 v41, v48, v113
	v_add_f32_e32 v40, v64, v40
	v_exp_f32_e32 v45, v41
	v_sub_f32_e32 v41, v49, v113
	v_add_f32_e32 v40, v65, v40
	v_exp_f32_e32 v46, v41
	v_sub_f32_e32 v41, v50, v113
	v_add_f32_e32 v40, v66, v40
	v_exp_f32_e32 v47, v41
	v_sub_f32_e32 v41, v51, v113
	v_add_f32_e32 v40, v67, v40
	v_exp_f32_e32 v48, v41
	v_sub_f32_e32 v41, v52, v113
	v_add_f32_e32 v40, v45, v40
	v_exp_f32_e32 v49, v41
	v_sub_f32_e32 v41, v53, v113
	v_add_f32_e32 v40, v46, v40
	v_exp_f32_e32 v50, v41
	v_sub_f32_e32 v41, v54, v113
	v_add_f32_e32 v40, v47, v40
	v_exp_f32_e32 v51, v41
	v_sub_f32_e32 v41, v55, v113
	v_add_f32_e32 v40, v48, v40
	v_exp_f32_e32 v52, v41
	v_add_f32_e32 v40, v49, v40
	v_add_f32_e32 v40, v50, v40
	v_add_f32_e32 v40, v51, v40
	v_add_f32_e32 v41, v52, v40
	v_sub_f32_e32 v40, v56, v113
	v_exp_f32_e32 v40, v40
	v_cvt_pk_bf16_f32 v54, v100, v101
	v_cvt_pk_bf16_f32 v55, v102, v103
	v_cvt_pk_bf16_f32 v56, v108, v109
	v_sub_f32_e32 v36, v36, v113
	v_add_f32_e32 v42, v40, v41
	v_sub_f32_e32 v41, v57, v113
	v_cvt_pk_bf16_f32 v57, v110, v111
	ds_read2_b64 v[100:103], v105 offset1:4
	ds_read2_b64 v[108:111], v104 offset1:4
	ds_read2_b64 v[130:133], v107 offset1:4
	ds_read2_b64 v[134:137], v106 offset1:4
	v_cvt_pk_bf16_f32 v92, v92, v93
	v_cvt_pk_bf16_f32 v93, v94, v95
	v_cvt_pk_bf16_f32 v94, v96, v97
	v_cvt_pk_bf16_f32 v95, v98, v99
	ds_read2_b64 v[96:99], v105 offset0:8 offset1:12
	s_waitcnt lgkmcnt(4)
	v_mfma_f32_16x16x32_bf16 v[100:103], v[100:103], v[54:57], 0
	v_exp_f32_e32 v41, v41
	v_sub_f32_e32 v37, v37, v113
	v_exp_f32_e32 v37, v37
	s_waitcnt lgkmcnt(0)
	v_mfma_f32_16x16x32_bf16 v[96:99], v[96:99], v[92:95], v[100:103]
	s_nop 2
	ds_read2_b64 v[100:103], v104 offset0:8 offset1:12
	v_add_f32_e32 v43, v41, v42
	v_sub_f32_e32 v42, v58, v113
	v_mfma_f32_16x16x32_bf16 v[108:111], v[108:111], v[54:57], 0
	v_exp_f32_e32 v42, v42
	v_sub_f32_e32 v38, v38, v113
	v_exp_f32_e32 v38, v38
	s_waitcnt lgkmcnt(0)
	v_mfma_f32_16x16x32_bf16 v[100:103], v[100:103], v[92:95], v[108:111]
	v_add_f32_e32 v44, v42, v43
	s_nop 1
	ds_read2_b64 v[108:111], v107 offset0:8 offset1:12
	v_sub_f32_e32 v43, v59, v113
	v_mfma_f32_16x16x32_bf16 v[130:133], v[130:133], v[54:57], 0
	v_exp_f32_e32 v43, v43
	v_sub_f32_e32 v39, v39, v113
	v_exp_f32_e32 v39, v39
	s_waitcnt lgkmcnt(0)
	v_mfma_f32_16x16x32_bf16 v[108:111], v[108:111], v[92:95], v[130:133]
	v_add_f32_e32 v53, v43, v44
	s_nop 1
	ds_read2_b64 v[130:133], v106 offset0:8 offset1:12
	v_cvt_pk_bf16_f32 v84, v84, v85
	v_mfma_f32_16x16x32_bf16 v[54:57], v[134:137], v[54:57], 0
	v_cvt_pk_bf16_f32 v85, v86, v87
	v_cvt_pk_bf16_f32 v86, v88, v89
	v_cvt_pk_bf16_f32 v87, v90, v91
	s_waitcnt lgkmcnt(0)
	v_mfma_f32_16x16x32_bf16 v[54:57], v[130:133], v[92:95], v[54:57]
	ds_read2_b64 v[88:91], v105 offset0:16 offset1:20
	ds_read2_b64 v[92:95], v104 offset0:16 offset1:20
	v_exp_f32_e32 v44, v36
	s_waitcnt lgkmcnt(1)
	v_mfma_f32_16x16x32_bf16 v[88:91], v[88:91], v[84:87], v[96:99]
	s_nop 2
	ds_read2_b64 v[96:99], v107 offset0:16 offset1:20
	v_add_f32_e32 v36, v44, v53
	v_add_f32_e32 v36, v37, v36
	s_waitcnt lgkmcnt(1)
	v_mfma_f32_16x16x32_bf16 v[92:95], v[92:95], v[84:87], v[100:103]
	v_add_f32_e32 v36, v38, v36
	v_add_f32_e32 v36, v39, v36
	ds_bpermute_b32 v53, v121, v36
	ds_read2_b64 v[100:103], v106 offset0:16 offset1:20
	s_waitcnt lgkmcnt(2)
	v_mfma_f32_16x16x32_bf16 v[96:99], v[96:99], v[84:87], v[108:111]
	v_cvt_pk_bf16_f32 v76, v76, v77
	v_cvt_pk_bf16_f32 v77, v78, v79
	v_cvt_pk_bf16_f32 v78, v80, v81
	s_waitcnt lgkmcnt(0)
	v_mfma_f32_16x16x32_bf16 v[54:57], v[100:103], v[84:87], v[54:57]
	v_cvt_pk_bf16_f32 v79, v82, v83
	ds_read2_b64 v[80:83], v105 offset0:24 offset1:28
	ds_read2_b64 v[84:87], v104 offset0:24 offset1:28
	s_waitcnt lgkmcnt(1)
	v_mfma_f32_16x16x32_bf16 v[80:83], v[80:83], v[76:79], v[88:91]
	s_nop 2
	ds_read2_b64 v[88:91], v107 offset0:24 offset1:28
	v_add_f32_e32 v36, v36, v53
	ds_bpermute_b32 v53, v122, v36
	s_waitcnt lgkmcnt(2)
	v_mfma_f32_16x16x32_bf16 v[84:87], v[84:87], v[76:79], v[92:95]
	s_waitcnt lgkmcnt(0)
	v_add_f32_e32 v36, v36, v53
	s_nop 0
	ds_read2_b64 v[92:95], v106 offset0:24 offset1:28
	v_mfma_f32_16x16x32_bf16 v[88:91], v[88:91], v[76:79], v[96:99]
	v_cvt_pk_bf16_f32 v68, v68, v69
	v_cvt_pk_bf16_f32 v69, v70, v71
	v_cvt_pk_bf16_f32 v70, v72, v73
	s_waitcnt lgkmcnt(0)
	v_mfma_f32_16x16x32_bf16 v[54:57], v[92:95], v[76:79], v[54:57]
	v_cvt_pk_bf16_f32 v71, v74, v75
	ds_read2_b64 v[72:75], v105 offset0:32 offset1:36
	ds_read2_b64 v[76:79], v104 offset0:32 offset1:36
	s_waitcnt lgkmcnt(1)
	v_mfma_f32_16x16x32_bf16 v[72:75], v[72:75], v[68:71], v[80:83]
	s_nop 2
	ds_read2_b64 v[80:83], v107 offset0:32 offset1:36
	s_waitcnt lgkmcnt(1)
	v_mfma_f32_16x16x32_bf16 v[76:79], v[76:79], v[68:71], v[84:87]
	s_nop 2
	ds_read2_b64 v[84:87], v106 offset0:32 offset1:36
	s_waitcnt lgkmcnt(1)
	v_mfma_f32_16x16x32_bf16 v[80:83], v[80:83], v[68:71], v[88:91]
	v_cvt_pk_bf16_f32 v58, v60, v61
	v_cvt_pk_bf16_f32 v59, v62, v63
	v_cvt_pk_bf16_f32 v60, v64, v65
	s_waitcnt lgkmcnt(0)
	v_mfma_f32_16x16x32_bf16 v[54:57], v[84:87], v[68:71], v[54:57]
	v_cvt_pk_bf16_f32 v61, v66, v67
	ds_read2_b64 v[62:65], v105 offset0:40 offset1:44
	ds_read2_b64 v[66:69], v104 offset0:40 offset1:44
	s_waitcnt lgkmcnt(1)
	v_mfma_f32_16x16x32_bf16 v[62:65], v[62:65], v[58:61], v[72:75]
	s_nop 2
	ds_read2_b64 v[70:73], v107 offset0:40 offset1:44
	s_waitcnt lgkmcnt(1)
	v_mfma_f32_16x16x32_bf16 v[66:69], v[66:69], v[58:61], v[76:79]
	s_nop 2
	ds_read2_b64 v[74:77], v106 offset0:40 offset1:44
	s_waitcnt lgkmcnt(1)
	v_mfma_f32_16x16x32_bf16 v[70:73], v[70:73], v[58:61], v[80:83]
	v_cvt_pk_bf16_f32 v46, v45, v46
	v_cvt_pk_bf16_f32 v47, v47, v48
	v_cvt_pk_bf16_f32 v48, v49, v50
	s_waitcnt lgkmcnt(0)
	v_mfma_f32_16x16x32_bf16 v[54:57], v[74:77], v[58:61], v[54:57]
	v_cvt_pk_bf16_f32 v49, v51, v52
	ds_read2_b64 v[50:53], v105 offset0:48 offset1:52
	ds_read2_b64 v[58:61], v104 offset0:48 offset1:52
	s_waitcnt lgkmcnt(1)
	v_mfma_f32_16x16x32_bf16 v[50:53], v[50:53], v[46:49], v[62:65]
	s_nop 2
	ds_read2_b64 v[62:65], v107 offset0:48 offset1:52
	s_waitcnt lgkmcnt(1)
	v_mfma_f32_16x16x32_bf16 v[58:61], v[58:61], v[46:49], v[66:69]
	s_nop 2
	ds_read2_b64 v[66:69], v106 offset0:48 offset1:52
	s_waitcnt lgkmcnt(1)
	v_mfma_f32_16x16x32_bf16 v[62:65], v[62:65], v[46:49], v[70:73]
	v_cvt_pk_bf16_f32 v40, v40, v41
	v_cvt_pk_bf16_f32 v41, v42, v43
	v_cvt_pk_bf16_f32 v42, v44, v37
	s_waitcnt lgkmcnt(0)
	v_mfma_f32_16x16x32_bf16 v[46:49], v[66:69], v[46:49], v[54:57]
	v_cvt_pk_bf16_f32 v43, v38, v39
	s_nop 2
	ds_read2_b64 v[54:57], v105 offset0:56 offset1:60
	v_div_scale_f32 v37, s[10:11], v36, v36, 1.0
	s_waitcnt lgkmcnt(0)
	v_mfma_f32_16x16x32_bf16 v[50:53], v[54:57], v[40:43], v[50:53]
	ds_read2_b64 v[54:57], v104 offset0:56 offset1:60
	s_waitcnt lgkmcnt(0)
	v_mfma_f32_16x16x32_bf16 v[54:57], v[54:57], v[40:43], v[58:61]
	s_nop 2
	ds_read2_b64 v[58:61], v107 offset0:56 offset1:60
	s_waitcnt lgkmcnt(0)
	v_mfma_f32_16x16x32_bf16 v[58:61], v[58:61], v[40:43], v[62:65]
	s_nop 2
	ds_read2_b64 v[62:65], v106 offset0:56 offset1:60
	s_waitcnt lgkmcnt(0)
	v_mfma_f32_16x16x32_bf16 v[38:41], v[62:65], v[40:43], v[46:49]
	v_rcp_f32_e32 v42, v37
	s_nop 0
	v_fma_f32 v43, -v37, v42, 1.0
	v_fmac_f32_e32 v42, v43, v42
	v_div_scale_f32 v43, vcc, 1.0, v36, 1.0
	v_mul_f32_e32 v44, v43, v42
	v_fma_f32 v45, -v37, v44, v43
	v_fmac_f32_e32 v44, v45, v42
	v_fma_f32 v37, -v37, v44, v43
	v_div_fmas_f32 v37, v37, v42, v44
	v_div_fixup_f32 v44, v37, v36, 1.0
	v_lshlrev_b64 v[36:37], 11, v[114:115]
	v_lshl_add_u64 v[36:37], s[4:5], 0, v[36:37]
	v_mul_f32_e32 v42, v44, v50
	v_mul_f32_e32 v43, v44, v51
	v_lshl_add_u64 v[36:37], v[36:37], 0, s[36:37]
	v_cvt_pk_bf16_f32 v42, v42, v43
	v_mul_f32_e32 v43, v44, v52
	v_lshl_add_u64 v[36:37], v[36:37], 0, v[2:3]
	v_mul_f32_e32 v45, v44, v53
	v_cvt_pk_bf16_f32 v43, v43, v45
	global_store_dwordx2 v[36:37], v[42:43], off offset:1536
	v_mul_f32_e32 v42, v44, v54
	v_mul_f32_e32 v43, v44, v55
	v_cvt_pk_bf16_f32 v42, v42, v43
	v_mul_f32_e32 v43, v44, v56
	v_mul_f32_e32 v45, v44, v57
	v_cvt_pk_bf16_f32 v43, v43, v45
	global_store_dwordx2 v[36:37], v[42:43], off offset:1568
	v_mul_f32_e32 v42, v44, v58
	v_mul_f32_e32 v43, v44, v59
	v_cvt_pk_bf16_f32 v42, v42, v43
	v_mul_f32_e32 v43, v44, v60
	v_mul_f32_e32 v38, v44, v38
	v_mul_f32_e32 v39, v44, v39
	v_mul_f32_e32 v45, v44, v61
	v_cvt_pk_bf16_f32 v43, v43, v45
	global_store_dwordx2 v[36:37], v[42:43], off offset:1600
	v_cvt_pk_bf16_f32 v38, v38, v39
	v_mul_f32_e32 v39, v44, v40
	v_mul_f32_e32 v40, v44, v41
	v_cvt_pk_bf16_f32 v39, v39, v40
	global_store_dwordx2 v[36:37], v[38:39], off offset:1632
	s_barrier
	s_cbranch_scc0 .LBB0_616
.LBB0_614:
	s_and_b32 s9, s7, 0xffffff00
	v_add_u32_e32 v116, s9, v120
	s_and_b32 s9, s7, 0xc0
	s_lshl_b32 s36, s9, 1
	v_ashrrev_i32_e32 v117, 31, v116
	v_lshl_add_u64 v[36:37], v[0:1], 0, s[36:37]
	v_lshlrev_b64 v[38:39], 9, v[116:117]
	v_or_b32_e32 v114, 16, v116
	v_lshl_add_u64 v[38:39], v[36:37], 0, v[38:39]
	v_ashrrev_i32_e32 v115, 31, v114
	s_waitcnt vmcnt(0)
	global_load_dwordx4 v[108:111], v[38:39], off
	global_load_dwordx4 v[60:63], v[38:39], off offset:64
	v_lshlrev_b64 v[38:39], 9, v[114:115]
	v_lshl_add_u64 v[36:37], v[36:37], 0, v[38:39]
	global_load_dwordx4 v[40:43], v[36:37], off
	s_nop 0
	global_load_dwordx4 v[36:39], v[36:37], off offset:64
	ds_write_b128 v119, v[16:19]
	ds_write_b128 v119, v[12:15] offset:16
	ds_write_b128 v119, v[8:11] offset:32
	ds_write_b128 v119, v[4:7] offset:48
	ds_write_b16 v123, v20 offset:36864
	ds_write_b16_d16_hi v123, v20 offset:37392
	ds_write_b16 v123, v21 offset:37920
	ds_write_b16_d16_hi v123, v21 offset:38448
	ds_write_b16 v123, v22 offset:38976
	ds_write_b16_d16_hi v123, v22 offset:39504
	ds_write_b16 v123, v23 offset:40032
	ds_write_b16_d16_hi v123, v23 offset:40560
	ds_write_b16 v123, v24 offset:41088
	ds_write_b16_d16_hi v123, v24 offset:41616
	ds_write_b16 v123, v25 offset:42144
	ds_write_b16_d16_hi v123, v25 offset:42672
	ds_write_b16 v123, v26 offset:43200
	ds_write_b16_d16_hi v123, v26 offset:43728
	ds_write_b16 v123, v27 offset:44256
	ds_write_b16_d16_hi v123, v27 offset:44784
	ds_write_b16 v123, v28 offset:45312
	ds_write_b16_d16_hi v123, v28 offset:45840
	ds_write_b16 v123, v29 offset:46368
	ds_write_b16_d16_hi v123, v29 offset:46896
	ds_write_b16 v123, v30 offset:47424
	ds_write_b16_d16_hi v123, v30 offset:47952
	ds_write_b16 v123, v31 offset:48480
	ds_write_b16_d16_hi v123, v31 offset:49008
	ds_write_b16 v123, v32 offset:49536
	ds_write_b16_d16_hi v123, v32 offset:50064
	ds_write_b16 v123, v33 offset:50592
	ds_write_b16_d16_hi v123, v33 offset:51120
	ds_write_b16 v123, v34 offset:51648
	ds_write_b16_d16_hi v123, v34 offset:52176
	ds_write_b16 v123, v35 offset:52704
	ds_write_b16_d16_hi v123, v35 offset:53232
	s_waitcnt lgkmcnt(0)
	s_barrier
	s_add_i32 s9, s92, s6
	s_addk_i32 s9, 0xff40
	s_cmpk_gt_i32 s9, 0x1ff
	s_cbranch_scc1 .Lma0_dummy
	s_and_b32 s9, s8, 0xffffff00
	v_add_u32_e32 v4, s9, v118
	v_readlane_b32 s9, v243, 37
	s_add_i32 s9, s9, s7
	v_ashrrev_i32_e32 v5, 31, v4
	s_addk_i32 s9, 0xd000
	v_lshlrev_b64 v[4:5], 11, v[4:5]
	s_and_b32 s9, s9, 0xc0
	v_lshl_add_u64 v[4:5], s[0:1], 0, v[4:5]
	s_lshl_b32 s10, s9, 1
	s_mov_b32 s11, s37
	v_lshl_add_u64 v[4:5], v[4:5], 0, s[10:11]
	v_mov_b32_e32 v113, v3
	v_lshl_add_u64 v[32:33], v[4:5], 0, v[112:113]
	global_load_dwordx4 v[4:7], v[32:33], off offset:48
	global_load_dwordx4 v[8:11], v[32:33], off offset:32
	global_load_dwordx4 v[12:15], v[32:33], off offset:16
	global_load_dwordx4 v[16:19], v[32:33], off
	global_load_dwordx4 v[20:23], v[32:33], off offset:512
	global_load_dwordx4 v[24:27], v[32:33], off offset:528
	global_load_dwordx4 v[28:31], v[32:33], off offset:544
	s_nop 0
	global_load_dwordx4 v[32:35], v[32:33], off offset:560
	s_branch .LBB0_613
.Lma0_dummy:
	global_load_dwordx4 v[4:7], v[0:1], off
	global_load_dwordx4 v[8:11], v[0:1], off
	global_load_dwordx4 v[12:15], v[0:1], off
	global_load_dwordx4 v[16:19], v[0:1], off
	global_load_dwordx4 v[20:23], v[0:1], off
	global_load_dwordx4 v[24:27], v[0:1], off
	global_load_dwordx4 v[28:31], v[0:1], off
	global_load_dwordx4 v[32:35], v[0:1], off
	s_branch .LBB0_613
